# walks: the two half-workgroup jobs run one barrier apart (half 1 takes one extra barrier before its step loop, half 0 one after) so unlike step segments overlap
# speedup vs baseline: 1.0210x; 1.0210x over previous
.LBB0_443:
	v_mov_b32_e32 v33, v1
	v_lshl_add_u64 v[2:3], v[2:3], 1, v[40:41]
	v_lshl_add_u64 v[40:41], s[68:69], 0, v[32:33]
	v_lshl_add_u64 v[32:33], s[70:71], 0, v[0:1]
	s_movk_i32 s10, 0xffbe
	v_lshl_add_u64 v[32:33], v[46:47], 1, v[32:33]
	v_mov_b32_e32 v49, v1
	v_mul_lo_u32 v0, v186, s10
	s_movk_i32 s10, 0x840
	v_mul_u32_u24_e32 v55, 0x84, v42
	v_add_u32_e32 v56, 0x41, v84
	v_lshl_add_u64 v[42:43], v[34:35], 1, v[68:69]
	v_lshl_add_u64 v[44:45], v[44:45], 1, s[84:85]
	v_lshl_add_u64 v[46:47], v[32:33], 0, v[48:49]
	v_mul_lo_u32 v57, v186, s10
	s_mov_b64 s[10:11], 0
	s_waitcnt vmcnt(0)
	v_mov_b64_e32 v[48:49], v[28:29]
	v_mov_b64_e32 v[50:51], v[30:31]
	v_readfirstlane_b32 s19, v65
	s_cmp_eq_u32 s19, 1
	s_cbranch_scc0 .Lwoff_gla_a
	s_barrier
.Lwoff_gla_a:
	s_branch .LBB0_445
.LBB0_444:
	s_or_b64 exec, exec, s[14:15]
	s_setprio 0
	v_add_u32_e32 v0, -1, v0
	v_mov_b32_e32 v84, v83
	s_andn2_b64 exec, exec, s[10:11]
	s_cbranch_execz .LBB0_474

.LBB0_474:
	s_or_b64 exec, exec, s[10:11]
	v_readfirstlane_b32 s19, v65
	s_cmp_eq_u32 s19, 0
	s_cbranch_scc0 .Lwoff_gla_b
	s_barrier
.Lwoff_gla_b:
	s_and_b64 vcc, exec, s[28:29]
	s_cbranch_vccz .LBB0_476
	global_store_dwordx4 v[36:37], v[8:11], off
	global_store_dwordx4 v[36:37], v[4:7], off offset:16
	s_mov_b64 s[42:43], -1

.LBB0_511:
	v_or_b32_e32 v98, v46, v83
	s_movk_i32 s10, 0xffd4
	v_lshlrev_b32_e32 v46, 4, v98
	v_mov_b32_e32 v47, v1
	v_mul_lo_u32 v194, v186, s10
	s_movk_i32 s10, 0x580
	v_mul_u32_u24_e32 v192, 0x84, v53
	s_mov_b32 s18, 44
	v_add_u32_e32 v193, 44, v52
	v_mov_b32_e32 v99, v1
	v_lshl_add_u64 v[100:101], v[48:49], 1, v[50:51]
	v_lshl_add_u64 v[102:103], s[90:91], 0, v[46:47]
	v_mul_lo_u32 v195, v186, s10
	v_mov_b32_e32 v57, 0
	s_waitcnt vmcnt(0)
	v_mov_b32_e32 v91, v96
	v_mov_b64_e32 v[108:109], v[104:105]
	v_mov_b64_e32 v[110:111], v[106:107]
	v_readfirstlane_b32 s10, v65
	s_cmp_eq_u32 s10, 1
	s_cbranch_scc0 .Lwoff_ml_a
	s_barrier
.Lwoff_ml_a:
.LBB0_512:
	v_add_u32_e32 v196, 1, v52
	v_cmp_lt_i32_e32 vcc, v196, v193
	s_cbranch_vccz .Lml_pre_done
	v_cmp_gt_i32_e32 vcc, 3, v52
	s_nop 1
	v_cndmask_b32_e64 v46, v217, 3, vcc
	v_add3_u32 v46, v194, v46, s18
	v_subrev_u32_e32 v46, 45, v46
	v_cndmask_b32_e64 v46, v46, v196, s[62:63]
	v_add_u32_e32 v93, v46, v192
	v_mul_hi_i32 v46, v93, s7
	v_lshrrev_b32_e32 v47, 31, v46
	v_ashrrev_i32_e32 v46, 5, v46
	v_add_u32_e32 v46, v46, v47
	v_mul_lo_u32 v47, v46, s17
	v_sub_u32_e32 v47, v93, v47
	v_cmp_lt_i32_e32 vcc, 3, v47
	v_lshlrev_b32_e32 v47, 6, v47
	v_lshlrev_b32_e32 v48, 13, v46
	v_lshlrev_b32_e32 v49, 8, v46
	s_movk_i32 s19, 0xff00
	v_add3_u32 v48, v47, v48, s19
	s_mov_b32 s19, 0x8000
	v_add3_u32 v49, v49, v47, s19
	v_cndmask_b32_e32 v197, v49, v48, vcc
	v_mov_b64_e32 v[46:47], s[70:71]
	v_mad_i64_i32 v[50:51], s[14:15], v197, s74, v[46:47]
	v_mov_b32_e32 v47, v1
	v_lshl_add_u64 v[198:199], v[50:51], 0, v[0:1]
	v_mov_b32_e32 v46, v84
	v_lshl_add_u64 v[200:201], v[50:51], 0, v[46:47]
	v_mov_b32_e32 v46, v86
	v_lshl_add_u64 v[202:203], v[50:51], 0, v[46:47]
	v_mov_b32_e32 v46, v90
	v_lshl_add_u64 v[204:205], v[50:51], 0, v[46:47]
	v_mov_b32_e32 v46, v92
	v_lshl_add_u64 v[204:205], v[204:205], 0, v[46:47]
	v_lshl_add_u64 v[204:205], v[88:89], 1, v[204:205]
	v_mov_b32_e32 v46, v94
	v_lshl_add_u64 v[204:205], v[204:205], 0, v[46:47]
	v_add_co_u32_e32 v204, vcc, 0x1000, v204
	s_nop 1
	v_addc_co_u32_e32 v205, vcc, 0, v205, vcc
	v_add_u32_e32 v46, v197, v187
	v_ashrrev_i32_e32 v47, 31, v46
	v_lshlrev_b64 v[46:47], 7, v[46:47]
	v_lshl_add_u64 v[234:235], v[102:103], 0, v[46:47]
	v_lshl_add_u32 v93, v93, 1, v188
	v_lshl_or_b32 v46, v93, 3, v189
	v_ashrrev_i32_e32 v47, 31, v46
	v_lshl_add_u64 v[236:237], v[46:47], 2, s[86:87]
	v_add_u32_e32 v46, v197, v190
	v_ashrrev_i32_e32 v47, 31, v46
	v_lshl_add_u64 v[46:47], v[46:47], 3, v[98:99]
	v_lshl_add_u64 v[238:239], v[46:47], 4, s[90:91]
	v_lshl_add_u64 v[240:241], v[46:47], 2, s[88:89]
	v_ashrrev_i32_e32 v47, 31, v93
	v_mov_b32_e32 v46, v93
	v_lshlrev_b64 v[46:47], 2, v[46:47]
	v_or_b32_e32 v46, v46, v83
	s_movk_i32 s19, 0x180
	v_mad_u64_u32 v[242:243], s[14:15], v46, s19, v[76:77]
	v_mad_i32_i24 v243, v47, s19, v243
	v_add_u32_e32 v46, v197, v191
	v_mad_i64_i32 v[244:245], s[14:15], v46, s16, v[100:101]

.LBB0_555:
	v_readfirstlane_b32 s10, v65
	s_cmp_eq_u32 s10, 0
	s_cbranch_scc0 .Lwoff_ml_b
	s_barrier
